# MLA_Q and MLA_KV epilogues: per-row PART loads hoisted 4 rows ahead with counted vmcnt so stores stay in flight
# speedup vs baseline: 1.0010x; 1.0010x over previous
; __device__ __forceinline__ u32x4 pack8(f32x4 a, f32x4 b) { u32x4 w; w.x = cvt_pk_bf16(a[0], a[1]); w.y = cvt_pk_bf16(a[2], a[3]); w.z = cvt_pk_bf16(b[0], b[1]); w.w = cvt_pk_bf16(b[2], b[3]); return w; }
;     __device__ __forceinline__ void operator()(const f32x4 (&acc)[2][2][4][2], const pg8::Unit& u, int wr, int wc, int fr, int fq) const {
;     ...
;             const int h = u.pn;
; #pragma unroll
;             for (int ai = 0; ai < 2; ++ai)
; #pragma unroll
;                 for (int m = 0; m < 4; ++m) { const int row = row0 + ai * 128 + m * 16;
;                     const f32x4 pa = *(const f32x4*)(f0 + (size_t)row * 16 + 8), pb = *(const f32x4*)(f0 + (size_t)row * 16 + 12);
;                     const float ssq = ((pa[0] + pa[1]) + (pa[2] + pa[3])) + ((pb[0] + pb[1]) + (pb[2] + pb[3]));
;                     const float sc = 1.0f / sqrtf(ssq * (1.0f / 512.0f) + 1e-6f);
;                     { const f32x4 v0 = acc[ai][0][m][0] * sc, v1 = acc[ai][0][m][1] * sc; *(u32x4*)(o0 + (size_t)row * 2048 + h * 128 + wc * 32 + 8 * fq) = pack8(v0, v1); }
;                     { const f32x4 v0 = acc[ai][1][m][0] * sc, v1 = acc[ai][1][m][1] * sc; const int b = row >> 13, t = row & 8191, dv = wc * 32 + 8 * fq;
;                         bf16_t* vp = o1 + ((size_t)((b * 16 + h) * 128 + dv)) * 8192 + t; const u32x4 w = pack8(v0, v1);
;                         vp[0] = (bf16_t)(w.x & 0xffff); vp[8192] = (bf16_t)(w.x >> 16); vp[2 * 8192] = (bf16_t)(w.y & 0xffff); vp[3 * 8192] = (bf16_t)(w.y >> 16);
;                         vp[4 * 8192] = (bf16_t)(w.z & 0xffff); vp[5 * 8192] = (bf16_t)(w.z >> 16); vp[6 * 8192] = (bf16_t)(w.w & 0xffff); vp[7 * 8192] = (bf16_t)(w.w >> 16); }
.LBB0_741:
	s_lshl_b32 s29, s22, 8
	s_lshl_b32 s41, s4, 8
	s_add_i32 s29, s29, s65
	s_or_b32 s22, s41, s68
	v_or_b32_e32 v158, s29, v147
	v_or_b32_e32 v156, s22, v146
	s_cmp_lt_i32 s52, 4
	s_mov_b64 s[18:19], -1
	s_cbranch_scc1 .LBB0_1049
	s_cmp_lt_i32 s52, 6
	s_cbranch_scc1 .LBB0_880
	s_cmp_lt_i32 s52, 7
	s_cbranch_scc1 .LBB0_813
	s_cmp_lg_u32 s52, 7
	s_cbranch_scc0 .LBB0_746
	s_ashr_i32 s20, s29, 9
	s_and_b32 s20, s20, 0x1fffff0
	s_add_i32 s20, s20, s4
	v_lshl_or_b32 v128, s20, 7, v187
	v_ashrrev_i32_e32 v129, 31, v128
	v_ashrrev_i32_e32 v159, 31, v158
	v_lshlrev_b64 v[132:133], 14, v[128:129]
	v_lshlrev_b64 v[128:129], 6, v[158:159]
	v_lshl_add_u64 v[134:135], s[50:51], 0, v[128:129]
	v_lshlrev_b32_e32 v178, 6, v158
	v_add_u32_e32 v179, 0x2000, v178
	global_load_dwordx4 v[190:193], v178, s[50:51] offset:32
	global_load_dwordx4 v[194:197], v178, s[50:51] offset:48
	global_load_dwordx4 v[198:201], v178, s[50:51] offset:1056
	global_load_dwordx4 v[202:205], v178, s[50:51] offset:1072
	global_load_dwordx4 v[224:227], v178, s[50:51] offset:2080
	global_load_dwordx4 v[228:231], v178, s[50:51] offset:2096
	global_load_dwordx4 v[232:235], v178, s[50:51] offset:3104
	global_load_dwordx4 v[236:239], v178, s[50:51] offset:3120
	s_lshl_b32 s18, s4, 7
	s_ashr_i32 s19, s18, 31
	s_lshl_b64 s[18:19], s[18:19], 1
	v_mov_b32_e32 v155, v181
	v_and_b32_e32 v157, 0x1fcf, v158
	v_lshlrev_b32_e32 v180, 1, v157
	s_mov_b32 s34, 0xc000
	s_mov_b32 s23, 0x10000
	s_mov_b32 s35, 0x14000
	s_mov_b32 s46, 0x18000
	s_mov_b32 s47, 0x1c000
	s_waitcnt vmcnt(6)
	v_mov_b32_e32 v128, v190
	v_mov_b32_e32 v129, v191
	v_mov_b32_e32 v130, v192
	v_mov_b32_e32 v131, v193
	v_mov_b32_e32 v134, v194
	v_mov_b32_e32 v135, v195
	v_mov_b32_e32 v136, v196
	v_mov_b32_e32 v137, v197
	global_load_dwordx4 v[190:193], v179, s[50:51] offset:32
	global_load_dwordx4 v[194:197], v179, s[50:51] offset:48
	v_mov_b32_e32 v160, v128
	v_mov_b32_e32 v161, v134
	v_mov_b32_e32 v134, v129
	v_pk_add_f32 v[128:129], v[160:161], v[134:135]
	v_mov_b32_e32 v134, v130
	v_mov_b32_e32 v135, v136
	v_mov_b32_e32 v136, v131
	v_pk_add_f32 v[130:131], v[134:135], v[136:137]
	s_nop 0
	v_pk_add_f32 v[128:129], v[128:129], v[130:131]
	s_nop 0
	v_add_f32_e32 v128, v128, v129
	v_fmamk_f32 v128, v128, 0x3b000000, v219
	v_cmp_gt_f32_e32 vcc, s86, v128
	v_mul_f32_e32 v129, 0x4f800000, v128
	s_nop 0
	v_cndmask_b32_e32 v128, v128, v129, vcc
	v_sqrt_f32_e32 v129, v128
	s_nop 0
	v_add_u32_e32 v130, -1, v129
	v_fma_f32 v131, -v130, v129, v128
	v_cmp_ge_f32_e64 s[44:45], 0, v131
	v_add_u32_e32 v131, 1, v129
	s_nop 0
	v_cndmask_b32_e64 v130, v129, v130, s[44:45]
	v_fma_f32 v129, -v131, v129, v128
	v_cmp_lt_f32_e64 s[44:45], 0, v129
	s_nop 1
	v_cndmask_b32_e64 v129, v130, v131, s[44:45]
	v_mul_f32_e32 v130, 0x37800000, v129
	v_cndmask_b32_e32 v129, v129, v130, vcc
	v_cmp_class_f32_e32 vcc, v128, v215
	s_nop 1
	v_cndmask_b32_e32 v128, v129, v128, vcc
	v_div_scale_f32 v129, s[20:21], v128, v128, 1.0
	v_rcp_f32_e32 v130, v129
	s_nop 0
	v_fma_f32 v131, -v129, v130, 1.0
	v_fmac_f32_e32 v130, v131, v130
	v_div_scale_f32 v131, vcc, 1.0, v128, 1.0
	v_mul_f32_e32 v134, v131, v130
	v_fma_f32 v135, -v129, v134, v131
	v_fmac_f32_e32 v134, v135, v130
	v_fma_f32 v129, -v129, v134, v131
	v_div_fmas_f32 v129, v129, v130, v134
	v_div_fixup_f32 v134, v129, v128, 1.0
	v_pk_mul_f32 v[130:131], v[126:127], v[134:135] op_sel_hi:[1,0]
	v_pk_mul_f32 v[128:129], v[124:125], v[134:135] op_sel_hi:[1,0]
	v_pk_mul_f32 v[136:137], v[122:123], v[134:135] op_sel_hi:[1,0]
	v_pk_mul_f32 v[160:161], v[120:121], v[134:135] op_sel_hi:[1,0]
	v_cvt_pk_bf16_f32 v128, v128, v129
	v_cvt_pk_bf16_f32 v129, v130, v131
	s_nop 0
	v_cvt_pk_bf16_f32 v130, v160, v161
	v_cvt_pk_bf16_f32 v131, v136, v137
	v_lshlrev_b64 v[136:137], 12, v[158:159]
	v_lshl_add_u64 v[136:137], s[94:95], 0, v[136:137]
	v_lshl_add_u64 v[136:137], v[136:137], 0, s[18:19]
	v_lshl_add_u64 v[136:137], v[136:137], 0, s[74:75]
	v_lshl_add_u64 v[136:137], v[136:137], 0, v[154:155]
	global_store_dwordx4 v[136:137], v[128:131], off
	v_pk_mul_f32 v[136:137], v[116:117], v[134:135] op_sel_hi:[1,0]
	v_pk_mul_f32 v[160:161], v[114:115], v[134:135] op_sel_hi:[1,0]
	v_lshl_add_u64 v[128:129], s[54:55], 0, v[132:133]
	v_pk_mul_f32 v[130:131], v[118:119], v[134:135] op_sel_hi:[1,0]
	v_lshl_add_u64 v[132:133], v[128:129], 0, v[180:181]
	v_cvt_pk_bf16_f32 v136, v136, v137
	v_cvt_pk_bf16_f32 v137, v130, v131
	v_add_co_u32_e32 v130, vcc, s1, v132
	v_pk_mul_f32 v[134:135], v[112:113], v[134:135] op_sel_hi:[1,0]
	s_nop 0
	v_addc_co_u32_e32 v131, vcc, 0, v133, vcc
	v_cvt_pk_bf16_f32 v134, v134, v135
	v_cvt_pk_bf16_f32 v135, v160, v161
	global_store_short_d16_hi v[130:131], v136, off
	v_add_co_u32_e32 v130, vcc, s96, v132
	v_or_b32_e32 v160, 16, v158
	s_nop 0
	v_addc_co_u32_e32 v131, vcc, 0, v133, vcc
	global_store_short v[130:131], v137, off
	v_add_co_u32_e32 v130, vcc, s34, v132
	v_ashrrev_i32_e32 v161, 31, v160
	s_nop 0
	v_addc_co_u32_e32 v131, vcc, 0, v133, vcc
	global_store_short_d16_hi v[130:131], v137, off
	v_add_co_u32_e32 v130, vcc, s23, v132
	global_store_short v[132:133], v136, off
	s_nop 0
	v_addc_co_u32_e32 v131, vcc, 0, v133, vcc
	global_store_short v[130:131], v134, off
	v_add_co_u32_e32 v130, vcc, s35, v132
	s_nop 1
	v_addc_co_u32_e32 v131, vcc, 0, v133, vcc
	global_store_short_d16_hi v[130:131], v134, off
	v_add_co_u32_e32 v130, vcc, s46, v132
	s_nop 1
	v_addc_co_u32_e32 v131, vcc, 0, v133, vcc
	global_store_short v[130:131], v135, off
	v_add_co_u32_e32 v130, vcc, s47, v132
	s_nop 1
	v_addc_co_u32_e32 v131, vcc, 0, v133, vcc
	global_store_short_d16_hi v[130:131], v135, off
	v_lshlrev_b64 v[130:131], 6, v[160:161]
	v_lshl_add_u64 v[134:135], s[50:51], 0, v[130:131]
	s_waitcnt vmcnt(15)
; __device__ __forceinline__ u32x4 pack8(f32x4 a, f32x4 b) { u32x4 w; w.x = cvt_pk_bf16(a[0], a[1]); w.y = cvt_pk_bf16(a[2], a[3]); w.z = cvt_pk_bf16(b[0], b[1]); w.w = cvt_pk_bf16(b[2], b[3]); return w; }
;     __device__ __forceinline__ void operator()(const f32x4 (&acc)[2][2][4][2], const pg8::Unit& u, int wr, int wc, int fr, int fq) const {
;     ...
;                     const f32x4 pa = *(const f32x4*)(f0 + (size_t)row * 16 + 8), pb = *(const f32x4*)(f0 + (size_t)row * 16 + 12);
;                     const float ssq = ((pa[0] + pa[1]) + (pa[2] + pa[3])) + ((pb[0] + pb[1]) + (pb[2] + pb[3]));
;                     const float sc = 1.0f / sqrtf(ssq * (1.0f / 512.0f) + 1e-6f);
;                     { const f32x4 v0 = acc[ai][0][m][0] * sc, v1 = acc[ai][0][m][1] * sc; *(u32x4*)(o0 + (size_t)row * 2048 + h * 128 + wc * 32 + 8 * fq) = pack8(v0, v1); }
;                     { const f32x4 v0 = acc[ai][1][m][0] * sc, v1 = acc[ai][1][m][1] * sc; const int b = row >> 13, t = row & 8191, dv = wc * 32 + 8 * fq;
;                         bf16_t* vp = o1 + ((size_t)((b * 16 + h) * 128 + dv)) * 8192 + t; const u32x4 w = pack8(v0, v1);
;                         vp[0] = (bf16_t)(w.x & 0xffff); vp[8192] = (bf16_t)(w.x >> 16); vp[2 * 8192] = (bf16_t)(w.y & 0xffff); vp[3 * 8192] = (bf16_t)(w.y >> 16);
;                         vp[4 * 8192] = (bf16_t)(w.z & 0xffff); vp[5 * 8192] = (bf16_t)(w.z >> 16); vp[6 * 8192] = (bf16_t)(w.w & 0xffff); vp[7 * 8192] = (bf16_t)(w.w >> 16); }
	v_mov_b32_e32 v130, v198
	v_mov_b32_e32 v131, v199
	v_mov_b32_e32 v132, v200
	v_mov_b32_e32 v133, v201
	v_mov_b32_e32 v134, v202
	v_mov_b32_e32 v135, v203
	v_mov_b32_e32 v136, v204
	v_mov_b32_e32 v137, v205
	global_load_dwordx4 v[198:201], v179, s[50:51] offset:1056
	global_load_dwordx4 v[202:205], v179, s[50:51] offset:1072
	v_mov_b32_e32 v162, v130
	v_mov_b32_e32 v163, v134
	v_mov_b32_e32 v134, v131
	v_pk_add_f32 v[130:131], v[162:163], v[134:135]
	v_mov_b32_e32 v134, v132
	v_mov_b32_e32 v135, v136
	v_mov_b32_e32 v136, v133
	v_pk_add_f32 v[132:133], v[134:135], v[136:137]
	s_nop 0
	v_pk_add_f32 v[130:131], v[130:131], v[132:133]
	s_nop 0
	v_add_f32_e32 v130, v130, v131
	v_fmamk_f32 v130, v130, 0x3b000000, v219
	v_cmp_gt_f32_e32 vcc, s86, v130
	v_mul_f32_e32 v131, 0x4f800000, v130
	s_nop 0
	v_cndmask_b32_e32 v130, v130, v131, vcc
	v_sqrt_f32_e32 v131, v130
	s_nop 0
	v_add_u32_e32 v132, -1, v131
	v_fma_f32 v133, -v132, v131, v130
	v_cmp_ge_f32_e64 s[44:45], 0, v133
	v_add_u32_e32 v133, 1, v131
	s_nop 0
	v_cndmask_b32_e64 v132, v131, v132, s[44:45]
	v_fma_f32 v131, -v133, v131, v130
	v_cmp_lt_f32_e64 s[44:45], 0, v131
	s_nop 1
	v_cndmask_b32_e64 v131, v132, v133, s[44:45]
	v_mul_f32_e32 v132, 0x37800000, v131
	v_cndmask_b32_e32 v131, v131, v132, vcc
	v_cmp_class_f32_e32 vcc, v130, v215
	s_nop 1
	v_cndmask_b32_e32 v130, v131, v130, vcc
	v_div_scale_f32 v131, s[20:21], v130, v130, 1.0
	v_rcp_f32_e32 v132, v131
	s_movk_i32 s20, 0x1fdf
	v_bitop3_b32 v157, v158, s20, 16 bitop3:0xc8
	v_lshlrev_b32_e32 v180, 1, v157
	v_fma_f32 v133, -v131, v132, 1.0
	v_fmac_f32_e32 v132, v133, v132
	v_div_scale_f32 v133, vcc, 1.0, v130, 1.0
	v_mul_f32_e32 v134, v133, v132
	v_fma_f32 v135, -v131, v134, v133
	v_fmac_f32_e32 v134, v135, v132
	v_fma_f32 v131, -v131, v134, v133
	v_div_fmas_f32 v131, v131, v132, v134
	v_div_fixup_f32 v136, v131, v130, 1.0
	v_pk_mul_f32 v[132:133], v[110:111], v[136:137] op_sel_hi:[1,0]
	v_pk_mul_f32 v[130:131], v[108:109], v[136:137] op_sel_hi:[1,0]
	v_pk_mul_f32 v[134:135], v[106:107], v[136:137] op_sel_hi:[1,0]
	v_pk_mul_f32 v[162:163], v[104:105], v[136:137] op_sel_hi:[1,0]
	v_cvt_pk_bf16_f32 v130, v130, v131
	v_cvt_pk_bf16_f32 v131, v132, v133
	s_nop 0
	v_cvt_pk_bf16_f32 v132, v162, v163
	v_cvt_pk_bf16_f32 v133, v134, v135
	v_lshlrev_b64 v[134:135], 12, v[160:161]
	v_lshl_add_u64 v[134:135], s[94:95], 0, v[134:135]
	v_lshl_add_u64 v[134:135], v[134:135], 0, s[18:19]
	v_lshl_add_u64 v[134:135], v[134:135], 0, s[74:75]
	v_lshl_add_u64 v[134:135], v[134:135], 0, v[154:155]
	global_store_dwordx4 v[134:135], v[130:133], off
	v_pk_mul_f32 v[134:135], v[100:101], v[136:137] op_sel_hi:[1,0]
	v_lshl_add_u64 v[160:161], v[128:129], 0, v[180:181]
	v_pk_mul_f32 v[130:131], v[102:103], v[136:137] op_sel_hi:[1,0]
	v_cvt_pk_bf16_f32 v134, v134, v135
	v_pk_mul_f32 v[132:133], v[98:99], v[136:137] op_sel_hi:[1,0]
	v_cvt_pk_bf16_f32 v135, v130, v131
	v_add_co_u32_e32 v130, vcc, s1, v160
	v_pk_mul_f32 v[136:137], v[96:97], v[136:137] op_sel_hi:[1,0]
	s_nop 0
	v_addc_co_u32_e32 v131, vcc, 0, v161, vcc
	v_cvt_pk_bf16_f32 v136, v136, v137
	v_cvt_pk_bf16_f32 v132, v132, v133
	global_store_short_d16_hi v[130:131], v134, off
	v_add_co_u32_e32 v130, vcc, s96, v160
	global_store_short v[160:161], v134, off
	s_nop 0
	v_addc_co_u32_e32 v131, vcc, 0, v161, vcc
	global_store_short v[130:131], v135, off
	v_add_co_u32_e32 v130, vcc, s34, v160
	s_nop 1
	v_addc_co_u32_e32 v131, vcc, 0, v161, vcc
	global_store_short_d16_hi v[130:131], v135, off
	v_add_co_u32_e32 v130, vcc, s23, v160
	s_nop 1
	v_addc_co_u32_e32 v131, vcc, 0, v161, vcc
	global_store_short v[130:131], v136, off
	v_add_co_u32_e32 v130, vcc, s35, v160
	s_nop 1
	v_addc_co_u32_e32 v131, vcc, 0, v161, vcc
	global_store_short_d16_hi v[130:131], v136, off
	v_add_co_u32_e32 v130, vcc, s46, v160
	s_nop 1
	v_addc_co_u32_e32 v131, vcc, 0, v161, vcc
	global_store_short v[130:131], v132, off
	v_add_co_u32_e32 v130, vcc, s47, v160
	s_nop 1
	v_addc_co_u32_e32 v131, vcc, 0, v161, vcc
	global_store_short_d16_hi v[130:131], v132, off
	v_or_b32_e32 v130, 32, v158
	v_ashrrev_i32_e32 v131, 31, v130
	v_lshlrev_b64 v[132:133], 6, v[130:131]
	v_lshl_add_u64 v[132:133], s[50:51], 0, v[132:133]
	v_lshlrev_b64 v[130:131], 12, v[130:131]
	v_lshl_add_u64 v[130:131], s[94:95], 0, v[130:131]
	v_lshl_add_u64 v[130:131], v[130:131], 0, s[18:19]
	v_lshl_add_u64 v[130:131], v[130:131], 0, s[74:75]
	v_lshl_add_u64 v[130:131], v[130:131], 0, v[154:155]
	s_waitcnt vmcnt(24)
; __device__ __forceinline__ u32x4 pack8(f32x4 a, f32x4 b) { u32x4 w; w.x = cvt_pk_bf16(a[0], a[1]); w.y = cvt_pk_bf16(a[2], a[3]); w.z = cvt_pk_bf16(b[0], b[1]); w.w = cvt_pk_bf16(b[2], b[3]); return w; }
;     __device__ __forceinline__ void operator()(const f32x4 (&acc)[2][2][4][2], const pg8::Unit& u, int wr, int wc, int fr, int fq) const {
;     ...
;                     const f32x4 pa = *(const f32x4*)(f0 + (size_t)row * 16 + 8), pb = *(const f32x4*)(f0 + (size_t)row * 16 + 12);
;                     const float ssq = ((pa[0] + pa[1]) + (pa[2] + pa[3])) + ((pb[0] + pb[1]) + (pb[2] + pb[3]));
;                     const float sc = 1.0f / sqrtf(ssq * (1.0f / 512.0f) + 1e-6f);
;                     { const f32x4 v0 = acc[ai][0][m][0] * sc, v1 = acc[ai][0][m][1] * sc; *(u32x4*)(o0 + (size_t)row * 2048 + h * 128 + wc * 32 + 8 * fq) = pack8(v0, v1); }
;                     { const f32x4 v0 = acc[ai][1][m][0] * sc, v1 = acc[ai][1][m][1] * sc; const int b = row >> 13, t = row & 8191, dv = wc * 32 + 8 * fq;
;                         bf16_t* vp = o1 + ((size_t)((b * 16 + h) * 128 + dv)) * 8192 + t; const u32x4 w = pack8(v0, v1);
;                         vp[0] = (bf16_t)(w.x & 0xffff); vp[8192] = (bf16_t)(w.x >> 16); vp[2 * 8192] = (bf16_t)(w.y & 0xffff); vp[3 * 8192] = (bf16_t)(w.y >> 16);
;                         vp[4 * 8192] = (bf16_t)(w.z & 0xffff); vp[5 * 8192] = (bf16_t)(w.z >> 16); vp[6 * 8192] = (bf16_t)(w.w & 0xffff); vp[7 * 8192] = (bf16_t)(w.w >> 16); }
	v_mov_b32_e32 v134, v224
	v_mov_b32_e32 v135, v225
	v_mov_b32_e32 v136, v226
	v_mov_b32_e32 v137, v227
	v_mov_b32_e32 v160, v228
	v_mov_b32_e32 v161, v229
	v_mov_b32_e32 v162, v230
	v_mov_b32_e32 v163, v231
	global_load_dwordx4 v[224:227], v179, s[50:51] offset:2080
	global_load_dwordx4 v[228:231], v179, s[50:51] offset:2096
	v_mov_b32_e32 v132, v134
	v_mov_b32_e32 v133, v160
	v_mov_b32_e32 v160, v135
	v_mov_b32_e32 v134, v136
	v_mov_b32_e32 v135, v162
	v_mov_b32_e32 v162, v137
	v_pk_add_f32 v[132:133], v[132:133], v[160:161]
	v_pk_add_f32 v[134:135], v[134:135], v[162:163]
	s_nop 0
	v_pk_add_f32 v[132:133], v[132:133], v[134:135]
	s_nop 0
	v_add_f32_e32 v132, v132, v133
	v_fmamk_f32 v132, v132, 0x3b000000, v219
	v_cmp_gt_f32_e32 vcc, s86, v132
	v_mul_f32_e32 v133, 0x4f800000, v132
	s_nop 0
	v_cndmask_b32_e32 v132, v132, v133, vcc
	v_sqrt_f32_e32 v133, v132
	s_nop 0
	v_add_u32_e32 v134, -1, v133
	v_fma_f32 v135, -v134, v133, v132
	v_cmp_ge_f32_e64 s[44:45], 0, v135
	v_add_u32_e32 v135, 1, v133
	s_nop 0
	v_cndmask_b32_e64 v134, v133, v134, s[44:45]
	v_fma_f32 v133, -v135, v133, v132
	v_cmp_lt_f32_e64 s[44:45], 0, v133
	s_nop 1
	v_cndmask_b32_e64 v133, v134, v135, s[44:45]
	v_mul_f32_e32 v134, 0x37800000, v133
	v_cndmask_b32_e32 v133, v133, v134, vcc
	v_cmp_class_f32_e32 vcc, v132, v215
	s_nop 1
	v_cndmask_b32_e32 v132, v133, v132, vcc
	v_div_scale_f32 v133, s[20:21], v132, v132, 1.0
	v_rcp_f32_e32 v134, v133
	s_movk_i32 s20, 0x1fef
	v_bitop3_b32 v157, v158, s20, 32 bitop3:0xc8
	v_lshlrev_b32_e32 v180, 1, v157
	v_fma_f32 v135, -v133, v134, 1.0
	v_fmac_f32_e32 v134, v135, v134
	v_div_scale_f32 v135, vcc, 1.0, v132, 1.0
	v_mul_f32_e32 v136, v135, v134
	v_fma_f32 v137, -v133, v136, v135
	v_fmac_f32_e32 v136, v137, v134
	v_fma_f32 v133, -v133, v136, v135
	v_div_fmas_f32 v133, v133, v134, v136
	v_div_fixup_f32 v136, v133, v132, 1.0
	v_pk_mul_f32 v[134:135], v[94:95], v[136:137] op_sel_hi:[1,0]
	v_pk_mul_f32 v[132:133], v[92:93], v[136:137] op_sel_hi:[1,0]
	v_pk_mul_f32 v[160:161], v[90:91], v[136:137] op_sel_hi:[1,0]
	v_pk_mul_f32 v[162:163], v[88:89], v[136:137] op_sel_hi:[1,0]
	v_cvt_pk_bf16_f32 v132, v132, v133
	v_cvt_pk_bf16_f32 v133, v134, v135
	s_nop 0
	v_cvt_pk_bf16_f32 v134, v162, v163
	v_cvt_pk_bf16_f32 v135, v160, v161
	global_store_dwordx4 v[130:131], v[132:135], off
	v_pk_mul_f32 v[130:131], v[86:87], v[136:137] op_sel_hi:[1,0]
	v_lshl_add_u64 v[160:161], v[128:129], 0, v[180:181]
	v_pk_mul_f32 v[134:135], v[84:85], v[136:137] op_sel_hi:[1,0]
	v_pk_mul_f32 v[132:133], v[82:83], v[136:137] op_sel_hi:[1,0]
	v_cvt_pk_bf16_f32 v134, v134, v135
	v_cvt_pk_bf16_f32 v135, v130, v131
	v_add_co_u32_e32 v130, vcc, s1, v160
	v_pk_mul_f32 v[136:137], v[80:81], v[136:137] op_sel_hi:[1,0]
	s_nop 0
	v_addc_co_u32_e32 v131, vcc, 0, v161, vcc
	v_cvt_pk_bf16_f32 v136, v136, v137
	v_cvt_pk_bf16_f32 v132, v132, v133
	global_store_short_d16_hi v[130:131], v134, off
	v_add_co_u32_e32 v130, vcc, s96, v160
	global_store_short v[160:161], v134, off
	s_nop 0
	v_addc_co_u32_e32 v131, vcc, 0, v161, vcc
	global_store_short v[130:131], v135, off
	v_add_co_u32_e32 v130, vcc, s34, v160
	s_nop 1
	v_addc_co_u32_e32 v131, vcc, 0, v161, vcc
	global_store_short_d16_hi v[130:131], v135, off
	v_add_co_u32_e32 v130, vcc, s23, v160
	s_nop 1
	v_addc_co_u32_e32 v131, vcc, 0, v161, vcc
	global_store_short v[130:131], v136, off
	v_add_co_u32_e32 v130, vcc, s35, v160
	s_nop 1
	v_addc_co_u32_e32 v131, vcc, 0, v161, vcc
	global_store_short_d16_hi v[130:131], v136, off
	v_add_co_u32_e32 v130, vcc, s46, v160
	s_nop 1
	v_addc_co_u32_e32 v131, vcc, 0, v161, vcc
	global_store_short v[130:131], v132, off
	v_add_co_u32_e32 v130, vcc, s47, v160
	s_nop 1
	v_addc_co_u32_e32 v131, vcc, 0, v161, vcc
	global_store_short_d16_hi v[130:131], v132, off
	v_or_b32_e32 v130, 48, v158
	v_ashrrev_i32_e32 v131, 31, v130
	v_lshlrev_b64 v[132:133], 6, v[130:131]
	v_lshl_add_u64 v[132:133], s[50:51], 0, v[132:133]
	v_lshlrev_b64 v[130:131], 12, v[130:131]
	v_lshl_add_u64 v[130:131], s[94:95], 0, v[130:131]
	v_lshl_add_u64 v[130:131], v[130:131], 0, s[18:19]
	v_lshl_add_u64 v[130:131], v[130:131], 0, s[74:75]
	v_lshl_add_u64 v[130:131], v[130:131], 0, v[154:155]
	s_waitcnt vmcnt(33)
	v_mov_b32_e32 v134, v232
	v_mov_b32_e32 v135, v233
	v_mov_b32_e32 v136, v234
	v_mov_b32_e32 v137, v235
	v_mov_b32_e32 v160, v236
	v_mov_b32_e32 v161, v237
	v_mov_b32_e32 v162, v238
	v_mov_b32_e32 v163, v239
	global_load_dwordx4 v[232:235], v179, s[50:51] offset:3104
	global_load_dwordx4 v[236:239], v179, s[50:51] offset:3120
	v_mov_b32_e32 v132, v134
	v_mov_b32_e32 v133, v160
	v_mov_b32_e32 v160, v135
	v_mov_b32_e32 v134, v136
	v_mov_b32_e32 v135, v162
	v_mov_b32_e32 v162, v137
	v_pk_add_f32 v[132:133], v[132:133], v[160:161]
	v_pk_add_f32 v[134:135], v[134:135], v[162:163]
	s_nop 0
	v_pk_add_f32 v[132:133], v[132:133], v[134:135]
	s_nop 0
	v_add_f32_e32 v132, v132, v133
	v_fmamk_f32 v132, v132, 0x3b000000, v219
	v_cmp_gt_f32_e32 vcc, s86, v132
	v_mul_f32_e32 v133, 0x4f800000, v132
	s_nop 0
	v_cndmask_b32_e32 v132, v132, v133, vcc
	v_sqrt_f32_e32 v133, v132
	s_nop 0
	v_add_u32_e32 v134, -1, v133
	v_fma_f32 v135, -v134, v133, v132
	v_cmp_ge_f32_e64 s[44:45], 0, v135
	v_add_u32_e32 v135, 1, v133
	s_nop 0
	v_cndmask_b32_e64 v134, v133, v134, s[44:45]
	v_fma_f32 v133, -v135, v133, v132
	v_cmp_lt_f32_e64 s[44:45], 0, v133
	s_nop 1
	v_cndmask_b32_e64 v133, v134, v135, s[44:45]
	v_mul_f32_e32 v134, 0x37800000, v133
	v_cndmask_b32_e32 v133, v133, v134, vcc
	v_cmp_class_f32_e32 vcc, v132, v215
	s_nop 1
	v_cndmask_b32_e32 v132, v133, v132, vcc
	v_div_scale_f32 v133, s[20:21], v132, v132, 1.0
	v_rcp_f32_e32 v134, v133
	s_movk_i32 s20, 0x1fff
; __device__ __forceinline__ u32x4 pack8(f32x4 a, f32x4 b) { u32x4 w; w.x = cvt_pk_bf16(a[0], a[1]); w.y = cvt_pk_bf16(a[2], a[3]); w.z = cvt_pk_bf16(b[0], b[1]); w.w = cvt_pk_bf16(b[2], b[3]); return w; }
;     __device__ __forceinline__ void operator()(const f32x4 (&acc)[2][2][4][2], const pg8::Unit& u, int wr, int wc, int fr, int fq) const {
;     ...
;                 for (int m = 0; m < 4; ++m) { const int row = row0 + ai * 128 + m * 16;
;                     const f32x4 pa = *(const f32x4*)(f0 + (size_t)row * 16 + 8), pb = *(const f32x4*)(f0 + (size_t)row * 16 + 12);
;                     const float ssq = ((pa[0] + pa[1]) + (pa[2] + pa[3])) + ((pb[0] + pb[1]) + (pb[2] + pb[3]));
;                     const float sc = 1.0f / sqrtf(ssq * (1.0f / 512.0f) + 1e-6f);
;                     { const f32x4 v0 = acc[ai][0][m][0] * sc, v1 = acc[ai][0][m][1] * sc; *(u32x4*)(o0 + (size_t)row * 2048 + h * 128 + wc * 32 + 8 * fq) = pack8(v0, v1); }
;                     { const f32x4 v0 = acc[ai][1][m][0] * sc, v1 = acc[ai][1][m][1] * sc; const int b = row >> 13, t = row & 8191, dv = wc * 32 + 8 * fq;
;                         bf16_t* vp = o1 + ((size_t)((b * 16 + h) * 128 + dv)) * 8192 + t; const u32x4 w = pack8(v0, v1);
;                         vp[0] = (bf16_t)(w.x & 0xffff); vp[8192] = (bf16_t)(w.x >> 16); vp[2 * 8192] = (bf16_t)(w.y & 0xffff); vp[3 * 8192] = (bf16_t)(w.y >> 16);
;                         vp[4 * 8192] = (bf16_t)(w.z & 0xffff); vp[5 * 8192] = (bf16_t)(w.z >> 16); vp[6 * 8192] = (bf16_t)(w.w & 0xffff); vp[7 * 8192] = (bf16_t)(w.w >> 16); }
	v_bitop3_b32 v157, v158, s20, 48 bitop3:0xc8
	v_lshlrev_b32_e32 v180, 1, v157
	v_fma_f32 v135, -v133, v134, 1.0
	v_fmac_f32_e32 v134, v135, v134
	v_div_scale_f32 v135, vcc, 1.0, v132, 1.0
	v_mul_f32_e32 v136, v135, v134
	v_fma_f32 v137, -v133, v136, v135
	v_fmac_f32_e32 v136, v137, v134
	v_fma_f32 v133, -v133, v136, v135
	v_div_fmas_f32 v133, v133, v134, v136
	v_div_fixup_f32 v136, v133, v132, 1.0
	v_pk_mul_f32 v[134:135], v[78:79], v[136:137] op_sel_hi:[1,0]
	v_pk_mul_f32 v[132:133], v[76:77], v[136:137] op_sel_hi:[1,0]
	v_pk_mul_f32 v[160:161], v[74:75], v[136:137] op_sel_hi:[1,0]
	v_pk_mul_f32 v[162:163], v[72:73], v[136:137] op_sel_hi:[1,0]
	v_cvt_pk_bf16_f32 v132, v132, v133
	v_cvt_pk_bf16_f32 v133, v134, v135
	v_lshl_add_u64 v[128:129], v[128:129], 0, v[180:181]
	v_cvt_pk_bf16_f32 v134, v162, v163
	v_cvt_pk_bf16_f32 v135, v160, v161
	global_store_dwordx4 v[130:131], v[132:135], off
	v_pk_mul_f32 v[130:131], v[70:71], v[136:137] op_sel_hi:[1,0]
	s_nop 0
	v_pk_mul_f32 v[134:135], v[68:69], v[136:137] op_sel_hi:[1,0]
	v_pk_mul_f32 v[132:133], v[66:67], v[136:137] op_sel_hi:[1,0]
	v_cvt_pk_bf16_f32 v134, v134, v135
	v_cvt_pk_bf16_f32 v135, v130, v131
	v_add_co_u32_e32 v130, vcc, s1, v128
	v_pk_mul_f32 v[136:137], v[64:65], v[136:137] op_sel_hi:[1,0]
	s_nop 0
	v_addc_co_u32_e32 v131, vcc, 0, v129, vcc
	v_cvt_pk_bf16_f32 v136, v136, v137
	v_cvt_pk_bf16_f32 v132, v132, v133
	global_store_short_d16_hi v[130:131], v134, off
	v_add_co_u32_e32 v130, vcc, s96, v128
	global_store_short v[128:129], v134, off
	s_nop 0
	v_addc_co_u32_e32 v131, vcc, 0, v129, vcc
	global_store_short v[130:131], v135, off
	v_add_co_u32_e32 v130, vcc, s34, v128
	s_nop 1
	v_addc_co_u32_e32 v131, vcc, 0, v129, vcc
	global_store_short_d16_hi v[130:131], v135, off
	v_add_co_u32_e32 v130, vcc, s23, v128
	s_nop 1
	v_addc_co_u32_e32 v131, vcc, 0, v129, vcc
	global_store_short v[130:131], v136, off
	v_add_co_u32_e32 v130, vcc, s35, v128
	s_nop 1
	v_addc_co_u32_e32 v131, vcc, 0, v129, vcc
	global_store_short_d16_hi v[130:131], v136, off
	v_add_co_u32_e32 v130, vcc, s46, v128
	s_nop 1
	v_addc_co_u32_e32 v131, vcc, 0, v129, vcc
	v_add_co_u32_e32 v128, vcc, s47, v128
	global_store_short v[130:131], v132, off
	s_nop 0
	v_addc_co_u32_e32 v129, vcc, 0, v129, vcc
	global_store_short_d16_hi v[128:129], v132, off
	v_add_u32_e32 v128, 0x80, v158
	v_ashrrev_i32_e32 v129, 9, v128
	v_and_b32_e32 v129, 0x1fffff0, v129
	v_add_u32_e32 v129, s4, v129
	v_lshl_or_b32 v130, v129, 7, v187
	v_ashrrev_i32_e32 v129, 31, v128
	v_lshlrev_b64 v[132:133], 6, v[128:129]
	v_lshl_add_u64 v[132:133], s[50:51], 0, v[132:133]
	v_ashrrev_i32_e32 v131, 31, v130
	v_lshlrev_b64 v[130:131], 14, v[130:131]
	v_and_b32_e32 v157, 0x1fcf, v128
	v_lshlrev_b32_e32 v180, 1, v157
	s_waitcnt vmcnt(42)
	v_mov_b32_e32 v134, v190
	v_mov_b32_e32 v135, v191
	v_mov_b32_e32 v136, v192
	v_mov_b32_e32 v137, v193
	v_mov_b32_e32 v160, v194
	v_mov_b32_e32 v161, v195
	v_mov_b32_e32 v162, v196
	v_mov_b32_e32 v163, v197
	v_mov_b32_e32 v132, v134
	v_mov_b32_e32 v133, v160
	v_mov_b32_e32 v160, v135
	v_mov_b32_e32 v134, v136
	v_mov_b32_e32 v135, v162
	v_mov_b32_e32 v162, v137
	v_pk_add_f32 v[132:133], v[132:133], v[160:161]
	v_pk_add_f32 v[134:135], v[134:135], v[162:163]
	s_nop 0
	v_pk_add_f32 v[132:133], v[132:133], v[134:135]
	s_nop 0
	v_add_f32_e32 v132, v132, v133
	v_fmamk_f32 v132, v132, 0x3b000000, v219
	v_cmp_gt_f32_e32 vcc, s86, v132
	v_mul_f32_e32 v133, 0x4f800000, v132
	s_nop 0
	v_cndmask_b32_e32 v132, v132, v133, vcc
	v_sqrt_f32_e32 v133, v132
	s_nop 0
	v_add_u32_e32 v134, -1, v133
	v_fma_f32 v135, -v134, v133, v132
	v_cmp_ge_f32_e64 s[44:45], 0, v135
	v_add_u32_e32 v135, 1, v133
	s_nop 0
	v_cndmask_b32_e64 v134, v133, v134, s[44:45]
	v_fma_f32 v133, -v135, v133, v132
	v_cmp_lt_f32_e64 s[44:45], 0, v133
	s_nop 1
	v_cndmask_b32_e64 v133, v134, v135, s[44:45]
	v_mul_f32_e32 v134, 0x37800000, v133
	v_cndmask_b32_e32 v133, v133, v134, vcc
	v_cmp_class_f32_e32 vcc, v132, v215
	s_nop 1
	v_cndmask_b32_e32 v132, v133, v132, vcc
	v_div_scale_f32 v133, s[20:21], v132, v132, 1.0
	v_rcp_f32_e32 v134, v133
	s_nop 0
	v_fma_f32 v135, -v133, v134, 1.0
	v_fmac_f32_e32 v134, v135, v134
	v_div_scale_f32 v135, vcc, 1.0, v132, 1.0
	v_mul_f32_e32 v136, v135, v134
	v_fma_f32 v137, -v133, v136, v135
	v_fmac_f32_e32 v136, v137, v134
	v_fma_f32 v133, -v133, v136, v135
	v_div_fmas_f32 v133, v133, v134, v136
	v_div_fixup_f32 v136, v133, v132, 1.0
	v_pk_mul_f32 v[134:135], v[62:63], v[136:137] op_sel_hi:[1,0]
	v_pk_mul_f32 v[132:133], v[60:61], v[136:137] op_sel_hi:[1,0]
	v_pk_mul_f32 v[160:161], v[58:59], v[136:137] op_sel_hi:[1,0]
	v_pk_mul_f32 v[162:163], v[56:57], v[136:137] op_sel_hi:[1,0]
	v_cvt_pk_bf16_f32 v132, v132, v133
	v_cvt_pk_bf16_f32 v133, v134, v135
	s_nop 0
	v_cvt_pk_bf16_f32 v134, v162, v163
	v_cvt_pk_bf16_f32 v135, v160, v161
	v_lshlrev_b64 v[160:161], 12, v[128:129]
	v_lshl_add_u64 v[160:161], s[94:95], 0, v[160:161]
	v_lshl_add_u64 v[160:161], v[160:161], 0, s[18:19]
	v_lshl_add_u64 v[160:161], v[160:161], 0, s[74:75]
	v_lshl_add_u64 v[160:161], v[160:161], 0, v[154:155]
	v_lshl_add_u64 v[128:129], s[54:55], 0, v[130:131]
	global_store_dwordx4 v[160:161], v[132:135], off
	v_lshl_add_u64 v[130:131], v[128:129], 0, v[180:181]
	v_pk_mul_f32 v[160:161], v[50:51], v[136:137] op_sel_hi:[1,0]
	v_pk_mul_f32 v[132:133], v[54:55], v[136:137] op_sel_hi:[1,0]
	v_pk_mul_f32 v[134:135], v[52:53], v[136:137] op_sel_hi:[1,0]
	v_pk_mul_f32 v[136:137], v[48:49], v[136:137] op_sel_hi:[1,0]
	v_cvt_pk_bf16_f32 v134, v134, v135
	v_cvt_pk_bf16_f32 v135, v132, v133
	v_add_co_u32_e32 v132, vcc, s1, v130
	v_cvt_pk_bf16_f32 v136, v136, v137
	v_cvt_pk_bf16_f32 v137, v160, v161
	global_store_short v[130:131], v134, off
	s_nop 0
	v_addc_co_u32_e32 v133, vcc, 0, v131, vcc
	global_store_short_d16_hi v[132:133], v134, off
	v_add_co_u32_e32 v132, vcc, s96, v130
	s_nop 1
	v_addc_co_u32_e32 v133, vcc, 0, v131, vcc
	global_store_short v[132:133], v135, off
	v_add_co_u32_e32 v132, vcc, s34, v130
	s_nop 1
	v_addc_co_u32_e32 v133, vcc, 0, v131, vcc
	global_store_short_d16_hi v[132:133], v135, off
	v_add_co_u32_e32 v132, vcc, s23, v130
	s_nop 1
	v_addc_co_u32_e32 v133, vcc, 0, v131, vcc
	global_store_short v[132:133], v136, off
	v_add_co_u32_e32 v132, vcc, s35, v130
	s_nop 1
	v_addc_co_u32_e32 v133, vcc, 0, v131, vcc
	global_store_short_d16_hi v[132:133], v136, off
	v_add_co_u32_e32 v132, vcc, s46, v130
	s_nop 1
	v_addc_co_u32_e32 v133, vcc, 0, v131, vcc
	v_add_co_u32_e32 v130, vcc, s47, v130
	global_store_short v[132:133], v137, off
	s_nop 0
	v_addc_co_u32_e32 v131, vcc, 0, v131, vcc
	global_store_short_d16_hi v[130:131], v137, off
	v_add_u32_e32 v130, 0x90, v158
	v_ashrrev_i32_e32 v131, 31, v130
	v_lshlrev_b64 v[132:133], 6, v[130:131]
	v_lshl_add_u64 v[132:133], s[50:51], 0, v[132:133]
	s_waitcnt vmcnt(49)
; __device__ __forceinline__ u32x4 pack8(f32x4 a, f32x4 b) { u32x4 w; w.x = cvt_pk_bf16(a[0], a[1]); w.y = cvt_pk_bf16(a[2], a[3]); w.z = cvt_pk_bf16(b[0], b[1]); w.w = cvt_pk_bf16(b[2], b[3]); return w; }
;     __device__ __forceinline__ void operator()(const f32x4 (&acc)[2][2][4][2], const pg8::Unit& u, int wr, int wc, int fr, int fq) const {
;     ...
;                 for (int m = 0; m < 4; ++m) { const int row = row0 + ai * 128 + m * 16;
;                     const f32x4 pa = *(const f32x4*)(f0 + (size_t)row * 16 + 8), pb = *(const f32x4*)(f0 + (size_t)row * 16 + 12);
;                     const float ssq = ((pa[0] + pa[1]) + (pa[2] + pa[3])) + ((pb[0] + pb[1]) + (pb[2] + pb[3]));
;                     const float sc = 1.0f / sqrtf(ssq * (1.0f / 512.0f) + 1e-6f);
;                     { const f32x4 v0 = acc[ai][0][m][0] * sc, v1 = acc[ai][0][m][1] * sc; *(u32x4*)(o0 + (size_t)row * 2048 + h * 128 + wc * 32 + 8 * fq) = pack8(v0, v1); }
;                     { const f32x4 v0 = acc[ai][1][m][0] * sc, v1 = acc[ai][1][m][1] * sc; const int b = row >> 13, t = row & 8191, dv = wc * 32 + 8 * fq;
;                         bf16_t* vp = o1 + ((size_t)((b * 16 + h) * 128 + dv)) * 8192 + t; const u32x4 w = pack8(v0, v1);
;                         vp[0] = (bf16_t)(w.x & 0xffff); vp[8192] = (bf16_t)(w.x >> 16); vp[2 * 8192] = (bf16_t)(w.y & 0xffff); vp[3 * 8192] = (bf16_t)(w.y >> 16);
;                         vp[4 * 8192] = (bf16_t)(w.z & 0xffff); vp[5 * 8192] = (bf16_t)(w.z >> 16); vp[6 * 8192] = (bf16_t)(w.w & 0xffff); vp[7 * 8192] = (bf16_t)(w.w >> 16); }
	v_mov_b32_e32 v134, v198
	v_mov_b32_e32 v135, v199
	v_mov_b32_e32 v136, v200
	v_mov_b32_e32 v137, v201
	v_mov_b32_e32 v160, v202
	v_mov_b32_e32 v161, v203
	v_mov_b32_e32 v162, v204
	v_mov_b32_e32 v163, v205
	v_mov_b32_e32 v132, v134
	v_mov_b32_e32 v133, v160
	v_mov_b32_e32 v160, v135
	v_mov_b32_e32 v134, v136
	v_mov_b32_e32 v135, v162
	v_mov_b32_e32 v162, v137
	v_pk_add_f32 v[132:133], v[132:133], v[160:161]
	v_pk_add_f32 v[134:135], v[134:135], v[162:163]
	s_nop 0
	v_pk_add_f32 v[132:133], v[132:133], v[134:135]
	s_nop 0
	v_add_f32_e32 v132, v132, v133
	v_fmamk_f32 v132, v132, 0x3b000000, v219
	v_cmp_gt_f32_e32 vcc, s86, v132
	v_mul_f32_e32 v133, 0x4f800000, v132
	s_nop 0
	v_cndmask_b32_e32 v132, v132, v133, vcc
	v_sqrt_f32_e32 v133, v132
	s_nop 0
	v_add_u32_e32 v134, -1, v133
	v_fma_f32 v135, -v134, v133, v132
	v_cmp_ge_f32_e64 s[44:45], 0, v135
	v_add_u32_e32 v135, 1, v133
	s_nop 0
	v_cndmask_b32_e64 v134, v133, v134, s[44:45]
	v_fma_f32 v133, -v135, v133, v132
	v_cmp_lt_f32_e64 s[44:45], 0, v133
	s_nop 1
	v_cndmask_b32_e64 v133, v134, v135, s[44:45]
	v_mul_f32_e32 v134, 0x37800000, v133
	v_cndmask_b32_e32 v133, v133, v134, vcc
	v_cmp_class_f32_e32 vcc, v132, v215
	s_nop 1
	v_cndmask_b32_e32 v132, v133, v132, vcc
	v_div_scale_f32 v133, s[20:21], v132, v132, 1.0
	v_rcp_f32_e32 v134, v133
	s_nop 0
	v_fma_f32 v135, -v133, v134, 1.0
	v_fmac_f32_e32 v134, v135, v134
	v_div_scale_f32 v135, vcc, 1.0, v132, 1.0
	v_mul_f32_e32 v136, v135, v134
	v_fma_f32 v137, -v133, v136, v135
	v_fmac_f32_e32 v136, v137, v134
	v_fma_f32 v133, -v133, v136, v135
	v_div_fmas_f32 v133, v133, v134, v136
	v_div_fixup_f32 v136, v133, v132, 1.0
	v_pk_mul_f32 v[134:135], v[46:47], v[136:137] op_sel_hi:[1,0]
	v_pk_mul_f32 v[132:133], v[44:45], v[136:137] op_sel_hi:[1,0]
	v_pk_mul_f32 v[160:161], v[42:43], v[136:137] op_sel_hi:[1,0]
	v_pk_mul_f32 v[162:163], v[40:41], v[136:137] op_sel_hi:[1,0]
	v_cvt_pk_bf16_f32 v132, v132, v133
	v_cvt_pk_bf16_f32 v133, v134, v135
	s_nop 0
	v_cvt_pk_bf16_f32 v134, v162, v163
	v_cvt_pk_bf16_f32 v135, v160, v161
	v_lshlrev_b64 v[160:161], 12, v[130:131]
	v_lshl_add_u64 v[160:161], s[94:95], 0, v[160:161]
	v_lshl_add_u64 v[160:161], v[160:161], 0, s[18:19]
	v_lshl_add_u64 v[160:161], v[160:161], 0, s[74:75]
	v_and_b32_e32 v130, 0x1fdf, v130
	v_lshl_add_u64 v[160:161], v[160:161], 0, v[154:155]
	v_lshlrev_b32_e32 v180, 1, v130
	global_store_dwordx4 v[160:161], v[132:135], off
	v_lshl_add_u64 v[130:131], v[128:129], 0, v[180:181]
	v_pk_mul_f32 v[160:161], v[34:35], v[136:137] op_sel_hi:[1,0]
	v_pk_mul_f32 v[132:133], v[38:39], v[136:137] op_sel_hi:[1,0]
	v_pk_mul_f32 v[134:135], v[36:37], v[136:137] op_sel_hi:[1,0]
	v_pk_mul_f32 v[136:137], v[32:33], v[136:137] op_sel_hi:[1,0]
	v_cvt_pk_bf16_f32 v134, v134, v135
	v_cvt_pk_bf16_f32 v135, v132, v133
	v_add_co_u32_e32 v132, vcc, s1, v130
	v_cvt_pk_bf16_f32 v136, v136, v137
	v_cvt_pk_bf16_f32 v137, v160, v161
	global_store_short v[130:131], v134, off
	s_nop 0
	v_addc_co_u32_e32 v133, vcc, 0, v131, vcc
	global_store_short_d16_hi v[132:133], v134, off
	v_add_co_u32_e32 v132, vcc, s96, v130
	s_nop 1
	v_addc_co_u32_e32 v133, vcc, 0, v131, vcc
	global_store_short v[132:133], v135, off
	v_add_co_u32_e32 v132, vcc, s34, v130
	s_nop 1
	v_addc_co_u32_e32 v133, vcc, 0, v131, vcc
	global_store_short_d16_hi v[132:133], v135, off
	v_add_co_u32_e32 v132, vcc, s23, v130
	s_nop 1
	v_addc_co_u32_e32 v133, vcc, 0, v131, vcc
	global_store_short v[132:133], v136, off
	v_add_co_u32_e32 v132, vcc, s35, v130
	s_nop 1
	v_addc_co_u32_e32 v133, vcc, 0, v131, vcc
	global_store_short_d16_hi v[132:133], v136, off
	v_add_co_u32_e32 v132, vcc, s46, v130
	s_nop 1
	v_addc_co_u32_e32 v133, vcc, 0, v131, vcc
	v_add_co_u32_e32 v130, vcc, s47, v130
	global_store_short v[132:133], v137, off
	s_nop 0
	v_addc_co_u32_e32 v131, vcc, 0, v131, vcc
	global_store_short_d16_hi v[130:131], v137, off
	v_add_u32_e32 v130, 0xa0, v158
	v_ashrrev_i32_e32 v131, 31, v130
	v_lshlrev_b64 v[132:133], 6, v[130:131]
	v_lshl_add_u64 v[132:133], s[50:51], 0, v[132:133]
	s_waitcnt vmcnt(47)
	v_mov_b32_e32 v134, v224
	v_mov_b32_e32 v135, v225
	v_mov_b32_e32 v136, v226
	v_mov_b32_e32 v137, v227
	v_mov_b32_e32 v160, v228
	v_mov_b32_e32 v161, v229
	v_mov_b32_e32 v162, v230
	v_mov_b32_e32 v163, v231
	v_mov_b32_e32 v132, v134
	v_mov_b32_e32 v133, v160
	v_mov_b32_e32 v160, v135
	v_mov_b32_e32 v134, v136
	v_mov_b32_e32 v135, v162
	v_mov_b32_e32 v162, v137
	v_pk_add_f32 v[132:133], v[132:133], v[160:161]
	v_pk_add_f32 v[134:135], v[134:135], v[162:163]
	s_nop 0
	v_pk_add_f32 v[132:133], v[132:133], v[134:135]
	s_nop 0
	v_add_f32_e32 v132, v132, v133
	v_fmamk_f32 v132, v132, 0x3b000000, v219
	v_cmp_gt_f32_e32 vcc, s86, v132
	v_mul_f32_e32 v133, 0x4f800000, v132
	s_nop 0
	v_cndmask_b32_e32 v132, v132, v133, vcc
	v_sqrt_f32_e32 v133, v132
	s_nop 0
	v_add_u32_e32 v134, -1, v133
	v_fma_f32 v135, -v134, v133, v132
	v_cmp_ge_f32_e64 s[44:45], 0, v135
	v_add_u32_e32 v135, 1, v133
	s_nop 0
	v_cndmask_b32_e64 v134, v133, v134, s[44:45]
	v_fma_f32 v133, -v135, v133, v132
	v_cmp_lt_f32_e64 s[44:45], 0, v133
	s_nop 1
	v_cndmask_b32_e64 v133, v134, v135, s[44:45]
	v_mul_f32_e32 v134, 0x37800000, v133
	v_cndmask_b32_e32 v133, v133, v134, vcc
	v_cmp_class_f32_e32 vcc, v132, v215
	s_nop 1
	v_cndmask_b32_e32 v132, v133, v132, vcc
	v_div_scale_f32 v133, s[20:21], v132, v132, 1.0
	v_rcp_f32_e32 v134, v133
	s_nop 0
	v_fma_f32 v135, -v133, v134, 1.0
	v_fmac_f32_e32 v134, v135, v134
	v_div_scale_f32 v135, vcc, 1.0, v132, 1.0
	v_mul_f32_e32 v136, v135, v134
	v_fma_f32 v137, -v133, v136, v135
	v_fmac_f32_e32 v136, v137, v134
	v_fma_f32 v133, -v133, v136, v135
	v_div_fmas_f32 v133, v133, v134, v136
; __device__ __forceinline__ u32x4 pack8(f32x4 a, f32x4 b) { u32x4 w; w.x = cvt_pk_bf16(a[0], a[1]); w.y = cvt_pk_bf16(a[2], a[3]); w.z = cvt_pk_bf16(b[0], b[1]); w.w = cvt_pk_bf16(b[2], b[3]); return w; }
;     __device__ __forceinline__ void operator()(const f32x4 (&acc)[2][2][4][2], const pg8::Unit& u, int wr, int wc, int fr, int fq) const {
;     ...
;                 for (int m = 0; m < 4; ++m) { const int row = row0 + ai * 128 + m * 16;
;                     const f32x4 pa = *(const f32x4*)(f0 + (size_t)row * 16 + 8), pb = *(const f32x4*)(f0 + (size_t)row * 16 + 12);
;                     const float ssq = ((pa[0] + pa[1]) + (pa[2] + pa[3])) + ((pb[0] + pb[1]) + (pb[2] + pb[3]));
;                     const float sc = 1.0f / sqrtf(ssq * (1.0f / 512.0f) + 1e-6f);
;                     { const f32x4 v0 = acc[ai][0][m][0] * sc, v1 = acc[ai][0][m][1] * sc; *(u32x4*)(o0 + (size_t)row * 2048 + h * 128 + wc * 32 + 8 * fq) = pack8(v0, v1); }
;                     { const f32x4 v0 = acc[ai][1][m][0] * sc, v1 = acc[ai][1][m][1] * sc; const int b = row >> 13, t = row & 8191, dv = wc * 32 + 8 * fq;
;                         bf16_t* vp = o1 + ((size_t)((b * 16 + h) * 128 + dv)) * 8192 + t; const u32x4 w = pack8(v0, v1);
;                         vp[0] = (bf16_t)(w.x & 0xffff); vp[8192] = (bf16_t)(w.x >> 16); vp[2 * 8192] = (bf16_t)(w.y & 0xffff); vp[3 * 8192] = (bf16_t)(w.y >> 16);
;                         vp[4 * 8192] = (bf16_t)(w.z & 0xffff); vp[5 * 8192] = (bf16_t)(w.z >> 16); vp[6 * 8192] = (bf16_t)(w.w & 0xffff); vp[7 * 8192] = (bf16_t)(w.w >> 16); }
	v_div_fixup_f32 v136, v133, v132, 1.0
	v_pk_mul_f32 v[134:135], v[30:31], v[136:137] op_sel_hi:[1,0]
	v_pk_mul_f32 v[132:133], v[28:29], v[136:137] op_sel_hi:[1,0]
	v_pk_mul_f32 v[160:161], v[26:27], v[136:137] op_sel_hi:[1,0]
	v_pk_mul_f32 v[162:163], v[24:25], v[136:137] op_sel_hi:[1,0]
	v_cvt_pk_bf16_f32 v132, v132, v133
	v_cvt_pk_bf16_f32 v133, v134, v135
	s_nop 0
	v_cvt_pk_bf16_f32 v134, v162, v163
	v_cvt_pk_bf16_f32 v135, v160, v161
	v_lshlrev_b64 v[160:161], 12, v[130:131]
	v_lshl_add_u64 v[160:161], s[94:95], 0, v[160:161]
	v_lshl_add_u64 v[160:161], v[160:161], 0, s[18:19]
	v_lshl_add_u64 v[160:161], v[160:161], 0, s[74:75]
	v_and_b32_e32 v130, 0x1fef, v130
	v_lshl_add_u64 v[160:161], v[160:161], 0, v[154:155]
	v_lshlrev_b32_e32 v180, 1, v130
	global_store_dwordx4 v[160:161], v[132:135], off
	v_lshl_add_u64 v[130:131], v[128:129], 0, v[180:181]
	v_pk_mul_f32 v[160:161], v[18:19], v[136:137] op_sel_hi:[1,0]
	v_pk_mul_f32 v[132:133], v[22:23], v[136:137] op_sel_hi:[1,0]
	v_pk_mul_f32 v[134:135], v[20:21], v[136:137] op_sel_hi:[1,0]
	v_pk_mul_f32 v[136:137], v[16:17], v[136:137] op_sel_hi:[1,0]
	v_cvt_pk_bf16_f32 v134, v134, v135
	v_cvt_pk_bf16_f32 v135, v132, v133
	v_add_co_u32_e32 v132, vcc, s1, v130
	v_cvt_pk_bf16_f32 v136, v136, v137
	v_cvt_pk_bf16_f32 v137, v160, v161
	global_store_short v[130:131], v134, off
	s_nop 0
	v_addc_co_u32_e32 v133, vcc, 0, v131, vcc
	global_store_short_d16_hi v[132:133], v134, off
	v_add_co_u32_e32 v132, vcc, s96, v130
	s_nop 1
	v_addc_co_u32_e32 v133, vcc, 0, v131, vcc
	global_store_short v[132:133], v135, off
	v_add_co_u32_e32 v132, vcc, s34, v130
	s_nop 1
	v_addc_co_u32_e32 v133, vcc, 0, v131, vcc
	global_store_short_d16_hi v[132:133], v135, off
	v_add_co_u32_e32 v132, vcc, s23, v130
	s_nop 1
	v_addc_co_u32_e32 v133, vcc, 0, v131, vcc
	global_store_short v[132:133], v136, off
	v_add_co_u32_e32 v132, vcc, s35, v130
	s_nop 1
	v_addc_co_u32_e32 v133, vcc, 0, v131, vcc
	global_store_short_d16_hi v[132:133], v136, off
	v_add_co_u32_e32 v132, vcc, s46, v130
	s_nop 1
	v_addc_co_u32_e32 v133, vcc, 0, v131, vcc
	v_add_co_u32_e32 v130, vcc, s47, v130
	global_store_short v[132:133], v137, off
	s_nop 0
	v_addc_co_u32_e32 v131, vcc, 0, v131, vcc
	global_store_short_d16_hi v[130:131], v137, off
	v_add_u32_e32 v130, 0xb0, v158
	v_ashrrev_i32_e32 v131, 31, v130
	v_lshlrev_b64 v[132:133], 6, v[130:131]
	v_lshl_add_u64 v[132:133], s[50:51], 0, v[132:133]
	s_waitcnt vmcnt(36)
	v_mov_b32_e32 v134, v232
	v_mov_b32_e32 v135, v233
	v_mov_b32_e32 v136, v234
	v_mov_b32_e32 v137, v235
	v_mov_b32_e32 v160, v236
	v_mov_b32_e32 v161, v237
	v_mov_b32_e32 v162, v238
	v_mov_b32_e32 v163, v239
	v_mov_b32_e32 v132, v134
	v_mov_b32_e32 v133, v160
	v_mov_b32_e32 v160, v135
	v_mov_b32_e32 v134, v136
	v_mov_b32_e32 v135, v162
	v_mov_b32_e32 v162, v137
	v_pk_add_f32 v[132:133], v[132:133], v[160:161]
	v_pk_add_f32 v[134:135], v[134:135], v[162:163]
	s_nop 0
	v_pk_add_f32 v[132:133], v[132:133], v[134:135]
	s_nop 0
	v_add_f32_e32 v132, v132, v133
	v_fmamk_f32 v132, v132, 0x3b000000, v219
	v_cmp_gt_f32_e32 vcc, s86, v132
	v_mul_f32_e32 v133, 0x4f800000, v132
	s_nop 0
	v_cndmask_b32_e32 v132, v132, v133, vcc
	v_sqrt_f32_e32 v133, v132
	s_nop 0
	v_add_u32_e32 v134, -1, v133
	v_fma_f32 v135, -v134, v133, v132
	v_cmp_ge_f32_e64 s[44:45], 0, v135
	v_add_u32_e32 v135, 1, v133
	s_nop 0
	v_cndmask_b32_e64 v134, v133, v134, s[44:45]
	v_fma_f32 v133, -v135, v133, v132
	v_cmp_lt_f32_e64 s[44:45], 0, v133
	s_nop 1
	v_cndmask_b32_e64 v133, v134, v135, s[44:45]
	v_mul_f32_e32 v134, 0x37800000, v133
	v_cndmask_b32_e32 v133, v133, v134, vcc
	v_cmp_class_f32_e32 vcc, v132, v215
	s_nop 1
	v_cndmask_b32_e32 v132, v133, v132, vcc
	v_div_scale_f32 v133, s[20:21], v132, v132, 1.0
	v_rcp_f32_e32 v134, v133
	s_nop 0
	v_fma_f32 v135, -v133, v134, 1.0
	v_fmac_f32_e32 v134, v135, v134
	v_div_scale_f32 v135, vcc, 1.0, v132, 1.0
	v_mul_f32_e32 v136, v135, v134
	v_fma_f32 v137, -v133, v136, v135
	v_fmac_f32_e32 v136, v137, v134
	v_fma_f32 v133, -v133, v136, v135
	v_div_fmas_f32 v133, v133, v134, v136
	v_div_fixup_f32 v160, v133, v132, 1.0
	v_pk_mul_f32 v[134:135], v[14:15], v[160:161] op_sel_hi:[1,0]
	v_pk_mul_f32 v[132:133], v[12:13], v[160:161] op_sel_hi:[1,0]
	v_pk_mul_f32 v[136:137], v[10:11], v[160:161] op_sel_hi:[1,0]
	v_pk_mul_f32 v[162:163], v[8:9], v[160:161] op_sel_hi:[1,0]
	v_cvt_pk_bf16_f32 v132, v132, v133
	v_cvt_pk_bf16_f32 v133, v134, v135
	s_nop 0
	v_cvt_pk_bf16_f32 v134, v162, v163
	v_cvt_pk_bf16_f32 v135, v136, v137
	v_lshlrev_b64 v[136:137], 12, v[130:131]
	v_lshl_add_u64 v[136:137], s[94:95], 0, v[136:137]
	v_and_b32_e32 v130, 0x1fff, v130
	v_lshl_add_u64 v[136:137], v[136:137], 0, s[18:19]
	v_lshlrev_b32_e32 v180, 1, v130
	v_lshl_add_u64 v[136:137], v[136:137], 0, s[74:75]
	v_lshl_add_u64 v[128:129], v[128:129], 0, v[180:181]
	v_lshl_add_u64 v[136:137], v[136:137], 0, v[154:155]
	v_add_co_u32_e32 v130, vcc, s1, v128
	global_store_dwordx4 v[136:137], v[132:135], off
	v_pk_mul_f32 v[136:137], v[4:5], v[160:161] op_sel_hi:[1,0]
	v_addc_co_u32_e32 v131, vcc, 0, v129, vcc
	v_pk_mul_f32 v[132:133], v[6:7], v[160:161] op_sel_hi:[1,0]
	v_pk_mul_f32 v[134:135], v[2:3], v[160:161] op_sel_hi:[1,0]
	v_pk_mul_f32 v[160:161], v[0:1], v[160:161] op_sel_hi:[1,0]
	v_cvt_pk_bf16_f32 v136, v136, v137
	v_cvt_pk_bf16_f32 v132, v132, v133
	s_mov_b64 s[18:19], 0
	v_cvt_pk_bf16_f32 v133, v160, v161
	v_cvt_pk_bf16_f32 v134, v134, v135
	global_store_short_d16_hi v[130:131], v136, off
	v_add_co_u32_e32 v130, vcc, s96, v128
	global_store_short v[128:129], v136, off
	s_nop 0
	v_addc_co_u32_e32 v131, vcc, 0, v129, vcc
	global_store_short v[130:131], v132, off
	v_add_co_u32_e32 v130, vcc, s34, v128
	s_nop 1
	v_addc_co_u32_e32 v131, vcc, 0, v129, vcc
	global_store_short_d16_hi v[130:131], v132, off
	v_add_co_u32_e32 v130, vcc, s23, v128
	s_nop 1
	v_addc_co_u32_e32 v131, vcc, 0, v129, vcc
	global_store_short v[130:131], v133, off
	v_add_co_u32_e32 v130, vcc, 0x14000, v128
	s_nop 1
	v_addc_co_u32_e32 v131, vcc, 0, v129, vcc
	global_store_short_d16_hi v[130:131], v133, off
	v_add_co_u32_e32 v130, vcc, 0x18000, v128
	s_nop 1
	v_addc_co_u32_e32 v131, vcc, 0, v129, vcc
	v_add_co_u32_e32 v128, vcc, 0x1c000, v128
	global_store_short v[130:131], v134, off
	s_nop 0
	v_addc_co_u32_e32 v129, vcc, 0, v129, vcc
	global_store_short_d16_hi v[128:129], v134, off
